# D1 fused-norm epilogue, q_lat tile: q gains loaded once instead of 32 load+wait round trips (both tile kinds now de-serialised)
# speedup vs baseline: 1.0057x; 1.0057x over previous
.LBB0_1491:
	s_or_b64 exec, exec, s[6:7]
	v_lshl_or_b32 v16, v148, 2, s48
	v_lshlrev_b32_e32 v20, 2, v16
	s_waitcnt vmcnt(0) lgkmcnt(0)
	s_barrier
	global_load_dwordx4 v[224:227], v20, s[24:25]
	global_load_dwordx4 v[228:231], v20, s[24:25] offset:64
	global_load_dwordx4 v[232:235], v20, s[24:25] offset:512
	global_load_dwordx4 v[236:239], v20, s[24:25] offset:576
	v_or_b32_e32 v22, 16, v128
	v_lshl_add_u32 v21, v22, 6, 0
	ds_read2_b64 v[142:145], v149 offset1:2
	ds_read2_b64 v[146:149], v149 offset0:4 offset1:6
	ds_read2_b64 v[150:153], v21 offset1:2
	ds_read2_b64 v[154:157], v21 offset0:4 offset1:6
	s_mov_b32 s6, 0x358637bd
	s_mov_b32 s8, 0x3b800000
	v_mov_b64_e32 v[18:19], s[6:7]
	s_waitcnt lgkmcnt(2)
	v_mov_b32_e32 v143, v146
	v_mov_b32_e32 v145, v148
	s_waitcnt lgkmcnt(0)
	v_mov_b32_e32 v151, v154
	v_mov_b32_e32 v153, v156
	v_pk_add_f32 v[142:143], v[142:143], v[144:145]
	v_pk_add_f32 v[146:147], v[150:151], v[152:153]
	v_mov_b32_e32 v145, v142
	v_mov_b32_e32 v144, v146
	v_mov_b32_e32 v142, v147
	v_pk_add_f32 v[142:143], v[144:145], v[142:143]
	s_mov_b32 s3, 0x800000
	v_pk_fma_f32 v[142:143], v[142:143], s[8:9], v[18:19] op_sel_hi:[1,0,0]
	s_ashr_i32 s27, s26, 31
	v_mul_f32_e32 v21, 0x4b800000, v143
	v_cmp_gt_f32_e32 vcc, s3, v143
	s_lshl_b64 s[10:11], s[26:27], 17
	s_add_u32 s6, s28, s10
	v_cndmask_b32_e32 v21, v143, v21, vcc
	v_rsq_f32_e32 v21, v21
	s_addc_u32 s7, s29, s11
	v_mov_b32_e32 v129, 0
	s_add_u32 s6, s6, 0x14000000
	v_mul_f32_e32 v23, 0x45800000, v21
	v_cndmask_b32_e32 v146, v21, v23, vcc
	v_lshlrev_b64 v[158:159], 9, v[128:129]
	s_addc_u32 s7, s7, 0
	v_pk_mul_f32 v[136:137], v[136:137], v[146:147] op_sel_hi:[1,0]
	v_pk_mul_f32 v[134:135], v[134:135], v[146:147] op_sel_hi:[1,0]
	v_lshlrev_b32_e32 v16, 1, v16
	v_mov_b32_e32 v17, v129
	v_lshl_add_u64 v[144:145], s[6:7], 0, v[158:159]
	v_lshl_add_u64 v[144:145], v[144:145], 0, v[16:17]
	v_pk_mul_f32 v[132:133], v[132:133], v[146:147] op_sel_hi:[1,0]
	v_pk_mul_f32 v[130:131], v[130:131], v[146:147] op_sel_hi:[1,0]
	v_pk_mul_f32 v[126:127], v[126:127], v[146:147] op_sel_hi:[1,0]
	v_pk_mul_f32 v[124:125], v[124:125], v[146:147] op_sel_hi:[1,0]
	v_pk_mul_f32 v[122:123], v[122:123], v[146:147] op_sel_hi:[1,0]
	v_pk_mul_f32 v[120:121], v[120:121], v[146:147] op_sel_hi:[1,0]
	v_mul_f32_e32 v21, 0x4b800000, v142
	v_cmp_gt_f32_e32 vcc, s3, v142
	v_mov_b32_e32 v23, v129
	v_lshlrev_b64 v[22:23], 9, v[22:23]
	v_cndmask_b32_e32 v21, v142, v21, vcc
	v_rsq_f32_e32 v21, v21
	v_lshl_add_u64 v[22:23], s[6:7], 0, v[22:23]
	v_lshl_add_u64 v[22:23], v[22:23], 0, v[16:17]
	s_waitcnt vmcnt(0)
	v_mov_b64_e32 v[138:139], v[224:225]
	v_mov_b64_e32 v[140:141], v[226:227]
	v_pk_mul_f32 v[134:135], v[140:141], v[134:135]
	v_pk_mul_f32 v[136:137], v[138:139], v[136:137]
	s_nop 0
	v_cvt_pk_bf16_f32 v136, v136, v137
	v_cvt_pk_bf16_f32 v137, v134, v135
	global_store_dwordx2 v[144:145], v[136:137], off
	v_mov_b64_e32 v[134:135], v[228:229]
	v_mov_b64_e32 v[136:137], v[230:231]
	v_pk_mul_f32 v[130:131], v[136:137], v[130:131]
	v_pk_mul_f32 v[132:133], v[134:135], v[132:133]
	s_nop 0
	v_cvt_pk_bf16_f32 v132, v132, v133
	v_cvt_pk_bf16_f32 v133, v130, v131
	global_store_dwordx2 v[144:145], v[132:133], off offset:32
	v_mov_b64_e32 v[130:131], v[232:233]
	v_mov_b64_e32 v[132:133], v[234:235]
	v_pk_mul_f32 v[124:125], v[132:133], v[124:125]
	v_pk_mul_f32 v[126:127], v[130:131], v[126:127]
	s_nop 0
	v_cvt_pk_bf16_f32 v126, v126, v127
	v_cvt_pk_bf16_f32 v127, v124, v125
	global_store_dwordx2 v[144:145], v[126:127], off offset:256
	v_mov_b64_e32 v[124:125], v[236:237]
	v_mov_b64_e32 v[126:127], v[238:239]
	v_pk_mul_f32 v[120:121], v[126:127], v[120:121]
	v_pk_mul_f32 v[122:123], v[124:125], v[122:123]
	v_mul_f32_e32 v124, 0x45800000, v21
	v_cvt_pk_bf16_f32 v122, v122, v123
	v_cvt_pk_bf16_f32 v123, v120, v121
	global_store_dwordx2 v[144:145], v[122:123], off offset:288
	v_mov_b64_e32 v[120:121], v[224:225]
	v_mov_b64_e32 v[122:123], v[226:227]
	v_cndmask_b32_e32 v124, v21, v124, vcc
	v_pk_mul_f32 v[116:117], v[116:117], v[124:125] op_sel_hi:[1,0]
	v_pk_mul_f32 v[118:119], v[118:119], v[124:125] op_sel_hi:[1,0]
	v_pk_mul_f32 v[112:113], v[112:113], v[124:125] op_sel_hi:[1,0]
	v_pk_mul_f32 v[114:115], v[114:115], v[124:125] op_sel_hi:[1,0]
	v_pk_mul_f32 v[110:111], v[110:111], v[124:125] op_sel_hi:[1,0]
	v_pk_mul_f32 v[108:109], v[108:109], v[124:125] op_sel_hi:[1,0]
	v_pk_mul_f32 v[106:107], v[106:107], v[124:125] op_sel_hi:[1,0]
	v_pk_mul_f32 v[104:105], v[104:105], v[124:125] op_sel_hi:[1,0]
	v_or_b32_e32 v124, 48, v128
	v_mov_b32_e32 v125, v129
	v_pk_mul_f32 v[118:119], v[122:123], v[118:119]
	v_pk_mul_f32 v[116:117], v[120:121], v[116:117]
	s_nop 0
	v_cvt_pk_bf16_f32 v116, v116, v117
	v_cvt_pk_bf16_f32 v117, v118, v119
	global_store_dwordx2 v[22:23], v[116:117], off
	v_mov_b64_e32 v[116:117], v[228:229]
	v_mov_b64_e32 v[118:119], v[230:231]
	v_pk_mul_f32 v[114:115], v[118:119], v[114:115]
	v_pk_mul_f32 v[112:113], v[116:117], v[112:113]
	s_nop 0
	v_cvt_pk_bf16_f32 v112, v112, v113
	v_cvt_pk_bf16_f32 v113, v114, v115
	global_store_dwordx2 v[22:23], v[112:113], off offset:32
	v_mov_b64_e32 v[112:113], v[232:233]
	v_mov_b64_e32 v[114:115], v[234:235]
	v_pk_mul_f32 v[108:109], v[114:115], v[108:109]
	v_pk_mul_f32 v[110:111], v[112:113], v[110:111]
	s_nop 0
	v_cvt_pk_bf16_f32 v110, v110, v111
	v_cvt_pk_bf16_f32 v111, v108, v109
	global_store_dwordx2 v[22:23], v[110:111], off offset:256
	v_mov_b64_e32 v[108:109], v[236:237]
	v_mov_b64_e32 v[110:111], v[238:239]
	v_pk_mul_f32 v[104:105], v[110:111], v[104:105]
	v_pk_mul_f32 v[106:107], v[108:109], v[106:107]
	s_nop 0
	v_cvt_pk_bf16_f32 v106, v106, v107
	v_cvt_pk_bf16_f32 v107, v104, v105
	global_store_dwordx2 v[22:23], v[106:107], off offset:288
	v_mov_b64_e32 v[104:105], v[224:225]
	v_mov_b64_e32 v[106:107], v[226:227]
	v_or_b32_e32 v22, 32, v128
	v_lshl_add_u32 v21, v22, 6, 0
	ds_read2_b64 v[108:111], v21 offset0:4 offset1:6
	s_waitcnt lgkmcnt(0)
	v_lshl_add_u32 v109, v124, 6, 0
	ds_read2_b64 v[112:115], v109 offset0:4 offset1:6
	ds_read2_b64 v[116:119], v21 offset1:2
	ds_read2_b64 v[120:123], v109 offset1:2
	v_mov_b32_e32 v23, v129
	v_lshlrev_b64 v[22:23], 9, v[22:23]
	s_waitcnt lgkmcnt(1)
	v_mov_b32_e32 v117, v108
	v_mov_b32_e32 v119, v110
	s_waitcnt lgkmcnt(0)
	v_mov_b32_e32 v121, v112
	v_mov_b32_e32 v123, v114
	v_pk_add_f32 v[108:109], v[116:117], v[118:119]
	v_pk_add_f32 v[110:111], v[120:121], v[122:123]
	v_mov_b32_e32 v113, v108
	v_mov_b32_e32 v112, v110
	v_mov_b32_e32 v108, v111
	v_pk_add_f32 v[108:109], v[112:113], v[108:109]
	v_lshl_add_u64 v[22:23], s[6:7], 0, v[22:23]
	v_pk_fma_f32 v[108:109], v[108:109], s[8:9], v[18:19] op_sel_hi:[1,0,0]
	v_lshl_add_u64 v[22:23], v[22:23], 0, v[16:17]
	v_mul_f32_e32 v21, 0x4b800000, v109
	v_cmp_gt_f32_e32 vcc, s3, v109
	s_nop 1
	v_cndmask_b32_e32 v21, v109, v21, vcc
	v_rsq_f32_e32 v21, v21
	s_nop 0
	v_mul_f32_e32 v109, 0x45800000, v21
	v_cndmask_b32_e32 v110, v21, v109, vcc
	v_pk_mul_f32 v[100:101], v[100:101], v[110:111] op_sel_hi:[1,0]
	v_pk_mul_f32 v[102:103], v[102:103], v[110:111] op_sel_hi:[1,0]
	v_pk_mul_f32 v[96:97], v[96:97], v[110:111] op_sel_hi:[1,0]
	v_pk_mul_f32 v[98:99], v[98:99], v[110:111] op_sel_hi:[1,0]
	v_pk_mul_f32 v[94:95], v[94:95], v[110:111] op_sel_hi:[1,0]
	v_pk_mul_f32 v[92:93], v[92:93], v[110:111] op_sel_hi:[1,0]
	v_pk_mul_f32 v[90:91], v[90:91], v[110:111] op_sel_hi:[1,0]
	v_pk_mul_f32 v[88:89], v[88:89], v[110:111] op_sel_hi:[1,0]
	v_mul_f32_e32 v21, 0x4b800000, v108
	v_cmp_gt_f32_e32 vcc, s3, v108
	v_pk_mul_f32 v[102:103], v[106:107], v[102:103]
	v_pk_mul_f32 v[100:101], v[104:105], v[100:101]
	v_cndmask_b32_e32 v21, v108, v21, vcc
	v_cvt_pk_bf16_f32 v100, v100, v101
	v_cvt_pk_bf16_f32 v101, v102, v103
	global_store_dwordx2 v[22:23], v[100:101], off
	v_mov_b64_e32 v[100:101], v[228:229]
	v_mov_b64_e32 v[102:103], v[230:231]
	v_rsq_f32_e32 v21, v21
	v_pk_mul_f32 v[98:99], v[102:103], v[98:99]
	v_pk_mul_f32 v[96:97], v[100:101], v[96:97]
	s_nop 0
	v_cvt_pk_bf16_f32 v96, v96, v97
	v_cvt_pk_bf16_f32 v97, v98, v99
	global_store_dwordx2 v[22:23], v[96:97], off offset:32
	v_mov_b64_e32 v[96:97], v[232:233]
	v_mov_b64_e32 v[98:99], v[234:235]
	v_pk_mul_f32 v[92:93], v[98:99], v[92:93]
	v_pk_mul_f32 v[94:95], v[96:97], v[94:95]
	s_nop 0
	v_cvt_pk_bf16_f32 v94, v94, v95
	v_cvt_pk_bf16_f32 v95, v92, v93
	global_store_dwordx2 v[22:23], v[94:95], off offset:256
	v_mov_b64_e32 v[92:93], v[236:237]
	v_mov_b64_e32 v[94:95], v[238:239]
	v_pk_mul_f32 v[88:89], v[94:95], v[88:89]
	v_pk_mul_f32 v[90:91], v[92:93], v[90:91]
	v_mul_f32_e32 v92, 0x45800000, v21
	v_cvt_pk_bf16_f32 v90, v90, v91
	v_cvt_pk_bf16_f32 v91, v88, v89
	global_store_dwordx2 v[22:23], v[90:91], off offset:288
	v_mov_b64_e32 v[88:89], v[224:225]
	v_mov_b64_e32 v[90:91], v[226:227]
	v_cndmask_b32_e32 v92, v21, v92, vcc
	v_lshlrev_b64 v[22:23], 9, v[124:125]
	v_pk_mul_f32 v[84:85], v[84:85], v[92:93] op_sel_hi:[1,0]
	v_pk_mul_f32 v[86:87], v[86:87], v[92:93] op_sel_hi:[1,0]
	v_lshl_add_u64 v[22:23], s[6:7], 0, v[22:23]
	v_lshl_add_u64 v[22:23], v[22:23], 0, v[16:17]
	v_pk_mul_f32 v[80:81], v[80:81], v[92:93] op_sel_hi:[1,0]
	v_pk_mul_f32 v[82:83], v[82:83], v[92:93] op_sel_hi:[1,0]
	v_pk_mul_f32 v[78:79], v[78:79], v[92:93] op_sel_hi:[1,0]
	v_pk_mul_f32 v[76:77], v[76:77], v[92:93] op_sel_hi:[1,0]
	v_pk_mul_f32 v[74:75], v[74:75], v[92:93] op_sel_hi:[1,0]
	v_pk_mul_f32 v[72:73], v[72:73], v[92:93] op_sel_hi:[1,0]
	v_add_u32_e32 v92, 0x90, v128
	v_mov_b32_e32 v93, v129
	v_pk_mul_f32 v[86:87], v[90:91], v[86:87]
	v_pk_mul_f32 v[84:85], v[88:89], v[84:85]
	s_nop 0
	v_cvt_pk_bf16_f32 v84, v84, v85
	v_cvt_pk_bf16_f32 v85, v86, v87
	global_store_dwordx2 v[22:23], v[84:85], off
	v_mov_b64_e32 v[84:85], v[228:229]
	v_mov_b64_e32 v[86:87], v[230:231]
	v_pk_mul_f32 v[82:83], v[86:87], v[82:83]
	v_pk_mul_f32 v[80:81], v[84:85], v[80:81]
	s_nop 0
	v_cvt_pk_bf16_f32 v80, v80, v81
	v_cvt_pk_bf16_f32 v81, v82, v83
	global_store_dwordx2 v[22:23], v[80:81], off offset:32
	v_mov_b64_e32 v[80:81], v[232:233]
	v_mov_b64_e32 v[82:83], v[234:235]
	v_pk_mul_f32 v[76:77], v[82:83], v[76:77]
	v_pk_mul_f32 v[78:79], v[80:81], v[78:79]
	s_nop 0
	v_cvt_pk_bf16_f32 v78, v78, v79
	v_cvt_pk_bf16_f32 v79, v76, v77
	global_store_dwordx2 v[22:23], v[78:79], off offset:256
	v_mov_b64_e32 v[76:77], v[236:237]
	v_mov_b64_e32 v[78:79], v[238:239]
	v_pk_mul_f32 v[72:73], v[78:79], v[72:73]
	v_pk_mul_f32 v[74:75], v[76:77], v[74:75]
	s_nop 0
	v_cvt_pk_bf16_f32 v74, v74, v75
	v_cvt_pk_bf16_f32 v75, v72, v73
	global_store_dwordx2 v[22:23], v[74:75], off offset:288
	v_mov_b64_e32 v[72:73], v[224:225]
	v_mov_b64_e32 v[74:75], v[226:227]
	v_add_u32_e32 v22, 0x80, v128
	v_lshl_add_u32 v21, v22, 6, 0
	ds_read2_b64 v[76:79], v21 offset0:4 offset1:6
	s_waitcnt lgkmcnt(0)
	v_lshl_add_u32 v77, v92, 6, 0
	ds_read2_b64 v[80:83], v77 offset0:4 offset1:6
	ds_read2_b64 v[84:87], v21 offset1:2
	ds_read2_b64 v[88:91], v77 offset1:2
	v_mov_b32_e32 v23, v129
	v_lshlrev_b64 v[22:23], 9, v[22:23]
	s_waitcnt lgkmcnt(1)
	v_mov_b32_e32 v85, v76
	v_mov_b32_e32 v87, v78
	s_waitcnt lgkmcnt(0)
	v_mov_b32_e32 v89, v80
	v_mov_b32_e32 v91, v82
	v_pk_add_f32 v[76:77], v[84:85], v[86:87]
	v_pk_add_f32 v[78:79], v[88:89], v[90:91]
	v_mov_b32_e32 v81, v76
	v_mov_b32_e32 v80, v78
	v_mov_b32_e32 v76, v79
	v_pk_add_f32 v[76:77], v[80:81], v[76:77]
	v_lshl_add_u64 v[22:23], s[6:7], 0, v[22:23]
	v_pk_fma_f32 v[76:77], v[76:77], s[8:9], v[18:19] op_sel_hi:[1,0,0]
	v_lshl_add_u64 v[22:23], v[22:23], 0, v[16:17]
	v_mul_f32_e32 v21, 0x4b800000, v77
	v_cmp_gt_f32_e32 vcc, s3, v77
	s_nop 1
	v_cndmask_b32_e32 v21, v77, v21, vcc
	v_rsq_f32_e32 v21, v21
	s_nop 0
	v_mul_f32_e32 v77, 0x45800000, v21
	v_cndmask_b32_e32 v78, v21, v77, vcc
	v_pk_mul_f32 v[70:71], v[70:71], v[78:79] op_sel_hi:[1,0]
	v_pk_mul_f32 v[68:69], v[68:69], v[78:79] op_sel_hi:[1,0]
	v_pk_mul_f32 v[66:67], v[66:67], v[78:79] op_sel_hi:[1,0]
	v_pk_mul_f32 v[64:65], v[64:65], v[78:79] op_sel_hi:[1,0]
	v_pk_mul_f32 v[62:63], v[62:63], v[78:79] op_sel_hi:[1,0]
	v_pk_mul_f32 v[60:61], v[60:61], v[78:79] op_sel_hi:[1,0]
	v_pk_mul_f32 v[58:59], v[58:59], v[78:79] op_sel_hi:[1,0]
	v_pk_mul_f32 v[56:57], v[56:57], v[78:79] op_sel_hi:[1,0]
	v_mul_f32_e32 v21, 0x4b800000, v76
	v_cmp_gt_f32_e32 vcc, s3, v76
	v_pk_mul_f32 v[68:69], v[74:75], v[68:69]
	v_pk_mul_f32 v[70:71], v[72:73], v[70:71]
	v_cndmask_b32_e32 v21, v76, v21, vcc
	v_cvt_pk_bf16_f32 v70, v70, v71
	v_cvt_pk_bf16_f32 v71, v68, v69
	global_store_dwordx2 v[22:23], v[70:71], off
	v_mov_b64_e32 v[68:69], v[228:229]
	v_mov_b64_e32 v[70:71], v[230:231]
	v_rsq_f32_e32 v21, v21
	v_pk_mul_f32 v[64:65], v[70:71], v[64:65]
	v_pk_mul_f32 v[66:67], v[68:69], v[66:67]
	s_nop 0
	v_cvt_pk_bf16_f32 v66, v66, v67
	v_cvt_pk_bf16_f32 v67, v64, v65
	global_store_dwordx2 v[22:23], v[66:67], off offset:32
	v_mov_b64_e32 v[64:65], v[232:233]
	v_mov_b64_e32 v[66:67], v[234:235]
	v_pk_mul_f32 v[60:61], v[66:67], v[60:61]
	v_pk_mul_f32 v[62:63], v[64:65], v[62:63]
	s_nop 0
	v_cvt_pk_bf16_f32 v62, v62, v63
	v_cvt_pk_bf16_f32 v63, v60, v61
	global_store_dwordx2 v[22:23], v[62:63], off offset:256
	v_mov_b64_e32 v[60:61], v[236:237]
	v_mov_b64_e32 v[62:63], v[238:239]
	v_pk_mul_f32 v[56:57], v[62:63], v[56:57]
	v_pk_mul_f32 v[58:59], v[60:61], v[58:59]
	v_mul_f32_e32 v60, 0x45800000, v21
	v_cvt_pk_bf16_f32 v58, v58, v59
	v_cvt_pk_bf16_f32 v59, v56, v57
	global_store_dwordx2 v[22:23], v[58:59], off offset:288
	v_mov_b64_e32 v[56:57], v[224:225]
	v_mov_b64_e32 v[58:59], v[226:227]
	v_cndmask_b32_e32 v60, v21, v60, vcc
	v_lshlrev_b64 v[22:23], 9, v[92:93]
	v_pk_mul_f32 v[52:53], v[52:53], v[60:61] op_sel_hi:[1,0]
	v_pk_mul_f32 v[54:55], v[54:55], v[60:61] op_sel_hi:[1,0]
	v_lshl_add_u64 v[22:23], s[6:7], 0, v[22:23]
	v_lshl_add_u64 v[22:23], v[22:23], 0, v[16:17]
	v_pk_mul_f32 v[48:49], v[48:49], v[60:61] op_sel_hi:[1,0]
	v_pk_mul_f32 v[50:51], v[50:51], v[60:61] op_sel_hi:[1,0]
	v_pk_mul_f32 v[46:47], v[46:47], v[60:61] op_sel_hi:[1,0]
	v_pk_mul_f32 v[44:45], v[44:45], v[60:61] op_sel_hi:[1,0]
	v_pk_mul_f32 v[42:43], v[42:43], v[60:61] op_sel_hi:[1,0]
	v_pk_mul_f32 v[40:41], v[40:41], v[60:61] op_sel_hi:[1,0]
	v_pk_mul_f32 v[54:55], v[58:59], v[54:55]
	v_pk_mul_f32 v[52:53], v[56:57], v[52:53]
	s_nop 0
	v_cvt_pk_bf16_f32 v52, v52, v53
	v_cvt_pk_bf16_f32 v53, v54, v55
	global_store_dwordx2 v[22:23], v[52:53], off
	v_mov_b64_e32 v[52:53], v[228:229]
	v_mov_b64_e32 v[54:55], v[230:231]
	v_pk_mul_f32 v[50:51], v[54:55], v[50:51]
	v_pk_mul_f32 v[48:49], v[52:53], v[48:49]
	s_nop 0
	v_cvt_pk_bf16_f32 v48, v48, v49
	v_cvt_pk_bf16_f32 v49, v50, v51
	global_store_dwordx2 v[22:23], v[48:49], off offset:32
	v_mov_b64_e32 v[48:49], v[232:233]
	v_mov_b64_e32 v[50:51], v[234:235]
	v_pk_mul_f32 v[44:45], v[50:51], v[44:45]
	v_pk_mul_f32 v[46:47], v[48:49], v[46:47]
	s_nop 0
	v_cvt_pk_bf16_f32 v46, v46, v47
	v_cvt_pk_bf16_f32 v47, v44, v45
	global_store_dwordx2 v[22:23], v[46:47], off offset:256
	v_mov_b64_e32 v[44:45], v[236:237]
	v_mov_b64_e32 v[46:47], v[238:239]
	v_pk_mul_f32 v[40:41], v[46:47], v[40:41]
	v_pk_mul_f32 v[42:43], v[44:45], v[42:43]
	s_nop 0
	v_cvt_pk_bf16_f32 v42, v42, v43
	v_cvt_pk_bf16_f32 v43, v40, v41
	global_store_dwordx2 v[22:23], v[42:43], off offset:288
	v_mov_b64_e32 v[40:41], v[224:225]
	v_mov_b64_e32 v[42:43], v[226:227]
	v_add_u32_e32 v22, 0xa0, v128
	v_lshl_add_u32 v21, v22, 6, 0
	v_add_u32_e32 v128, 0xb0, v128
	ds_read2_b64 v[44:47], v21 offset0:4 offset1:6
	ds_read2_b64 v[48:51], v21 offset1:2
	v_lshl_add_u32 v21, v128, 6, 0
	ds_read2_b64 v[52:55], v21 offset0:4 offset1:6
	ds_read2_b64 v[56:59], v21 offset1:2
	v_mov_b32_e32 v23, v129
	s_waitcnt lgkmcnt(2)
	v_mov_b32_e32 v49, v44
	v_mov_b32_e32 v51, v46
	s_waitcnt lgkmcnt(0)
	v_mov_b32_e32 v57, v52
	v_mov_b32_e32 v59, v54
	v_pk_add_f32 v[44:45], v[48:49], v[50:51]
	v_pk_add_f32 v[46:47], v[56:57], v[58:59]
	v_mov_b32_e32 v49, v44
	v_mov_b32_e32 v48, v46
	v_mov_b32_e32 v44, v47
	v_pk_add_f32 v[44:45], v[48:49], v[44:45]
	v_lshlrev_b64 v[22:23], 9, v[22:23]
	v_pk_fma_f32 v[18:19], v[44:45], s[8:9], v[18:19] op_sel_hi:[1,0,0]
	v_lshl_add_u64 v[22:23], s[6:7], 0, v[22:23]
	v_mul_f32_e32 v21, 0x4b800000, v19
	v_cmp_gt_f32_e32 vcc, s3, v19
	v_lshl_add_u64 v[22:23], v[22:23], 0, v[16:17]
	s_nop 0
	v_cndmask_b32_e32 v19, v19, v21, vcc
	v_rsq_f32_e32 v19, v19
	s_nop 0
	v_mul_f32_e32 v21, 0x45800000, v19
	v_cndmask_b32_e32 v44, v19, v21, vcc
	v_pk_mul_f32 v[36:37], v[36:37], v[44:45] op_sel_hi:[1,0]
	v_pk_mul_f32 v[38:39], v[38:39], v[44:45] op_sel_hi:[1,0]
	v_pk_mul_f32 v[32:33], v[32:33], v[44:45] op_sel_hi:[1,0]
	v_pk_mul_f32 v[34:35], v[34:35], v[44:45] op_sel_hi:[1,0]
	v_pk_mul_f32 v[30:31], v[30:31], v[44:45] op_sel_hi:[1,0]
	v_pk_mul_f32 v[28:29], v[28:29], v[44:45] op_sel_hi:[1,0]
	v_pk_mul_f32 v[26:27], v[26:27], v[44:45] op_sel_hi:[1,0]
	v_pk_mul_f32 v[24:25], v[24:25], v[44:45] op_sel_hi:[1,0]
	v_mul_f32_e32 v19, 0x4b800000, v18
	v_cmp_gt_f32_e32 vcc, s3, v18
	v_pk_mul_f32 v[38:39], v[42:43], v[38:39]
	v_pk_mul_f32 v[36:37], v[40:41], v[36:37]
	v_cndmask_b32_e32 v18, v18, v19, vcc
	v_cvt_pk_bf16_f32 v36, v36, v37
	v_cvt_pk_bf16_f32 v37, v38, v39
	global_store_dwordx2 v[22:23], v[36:37], off
	v_mov_b64_e32 v[36:37], v[228:229]
	v_mov_b64_e32 v[38:39], v[230:231]
	v_rsq_f32_e32 v21, v18
	v_lshlrev_b64 v[18:19], 9, v[128:129]
	v_lshl_add_u64 v[18:19], s[6:7], 0, v[18:19]
	v_lshl_add_u64 v[18:19], v[18:19], 0, v[16:17]
	v_mul_f32_e32 v16, 0x45800000, v21
	v_pk_mul_f32 v[34:35], v[38:39], v[34:35]
	v_pk_mul_f32 v[32:33], v[36:37], v[32:33]
	s_nop 0
	v_cvt_pk_bf16_f32 v32, v32, v33
	v_cvt_pk_bf16_f32 v33, v34, v35
	global_store_dwordx2 v[22:23], v[32:33], off offset:32
	v_mov_b64_e32 v[32:33], v[232:233]
	v_mov_b64_e32 v[34:35], v[234:235]
	v_pk_mul_f32 v[28:29], v[34:35], v[28:29]
	v_pk_mul_f32 v[30:31], v[32:33], v[30:31]
	s_nop 0
	v_cvt_pk_bf16_f32 v30, v30, v31
	v_cvt_pk_bf16_f32 v31, v28, v29
	global_store_dwordx2 v[22:23], v[30:31], off offset:256
	v_mov_b64_e32 v[28:29], v[236:237]
	v_mov_b64_e32 v[30:31], v[238:239]
	v_pk_mul_f32 v[24:25], v[30:31], v[24:25]
	v_pk_mul_f32 v[26:27], v[28:29], v[26:27]
	s_nop 0
	v_cvt_pk_bf16_f32 v26, v26, v27
	v_cvt_pk_bf16_f32 v27, v24, v25
	global_store_dwordx2 v[22:23], v[26:27], off offset:288
	v_mov_b64_e32 v[22:23], v[224:225]
	v_mov_b64_e32 v[24:25], v[226:227]
	v_cndmask_b32_e32 v26, v21, v16, vcc
	v_pk_mul_f32 v[14:15], v[14:15], v[26:27] op_sel_hi:[1,0]
	v_pk_mul_f32 v[10:11], v[10:11], v[26:27] op_sel_hi:[1,0]
	v_pk_mul_f32 v[8:9], v[8:9], v[26:27] op_sel_hi:[1,0]
	v_pk_mul_f32 v[4:5], v[4:5], v[26:27] op_sel_hi:[1,0]
	v_pk_mul_f32 v[6:7], v[6:7], v[26:27] op_sel_hi:[1,0]
	v_pk_mul_f32 v[0:1], v[0:1], v[26:27] op_sel_hi:[1,0]
	v_pk_mul_f32 v[2:3], v[2:3], v[26:27] op_sel_hi:[1,0]
	v_pk_mul_f32 v[10:11], v[24:25], v[10:11]
	v_pk_mul_f32 v[14:15], v[22:23], v[14:15]
	s_nop 0
	v_cvt_pk_bf16_f32 v14, v14, v15
	v_cvt_pk_bf16_f32 v15, v10, v11
	global_store_dwordx2 v[18:19], v[14:15], off
	v_mov_b64_e32 v[14:15], v[228:229]
	v_mov_b64_e32 v[16:17], v[230:231]
	v_pk_mul_f32 v[10:11], v[12:13], v[26:27] op_sel_hi:[1,0]
	v_pk_mul_f32 v[8:9], v[16:17], v[8:9]
	v_pk_mul_f32 v[10:11], v[14:15], v[10:11]
	s_nop 0
	v_cvt_pk_bf16_f32 v10, v10, v11
	v_cvt_pk_bf16_f32 v11, v8, v9
	global_store_dwordx2 v[18:19], v[10:11], off offset:32
	v_mov_b64_e32 v[8:9], v[232:233]
	v_mov_b64_e32 v[10:11], v[234:235]
	v_pk_mul_f32 v[6:7], v[10:11], v[6:7]
	v_pk_mul_f32 v[4:5], v[8:9], v[4:5]
	s_nop 0
	v_cvt_pk_bf16_f32 v4, v4, v5
	v_cvt_pk_bf16_f32 v5, v6, v7
	global_store_dwordx2 v[18:19], v[4:5], off offset:256
	v_mov_b64_e32 v[4:5], v[236:237]
	v_mov_b64_e32 v[6:7], v[238:239]
	v_pk_mul_f32 v[2:3], v[6:7], v[2:3]
	v_pk_mul_f32 v[0:1], v[4:5], v[0:1]
	s_nop 0
	v_cvt_pk_bf16_f32 v0, v0, v1
	v_cvt_pk_bf16_f32 v1, v2, v3
	global_store_dwordx2 v[18:19], v[0:1], off offset:288
